# v015 plus: differential-attention step replaces the per-lane recomputation of a wave-uniform mask by one scalar and-not
# baseline (speedup 1.0000x reference)
.LBB0_386:
	s_andn2_b64 s[38:39], exec, s[12:13]
	s_andn2_b64 vcc, exec, s[12:13]
	s_cbranch_vccnz .LBB0_388
	s_xor_b32 s12, s48, 1
	v_lshl_add_u64 v[12:13], v[180:181], 0, s[18:19]
	s_mul_i32 s12, s12, 0x8800
	v_add_co_u32_e32 v14, vcc, 0x28010000, v12
	v_add_u32_e32 v10, s12, v190
	s_nop 0
	v_addc_co_u32_e32 v15, vcc, 0, v13, vcc
	s_waitcnt vmcnt(0)
	ds_write_b128 v10, v[160:163]
	ds_write_b128 v10, v[164:167] offset:8704
	ds_write_b128 v10, v[168:171] offset:17408
	ds_write_b128 v10, v[172:175] offset:26112
	v_add_co_u32_e32 v164, vcc, 0x28014000, v12
	s_nop 1
	v_addc_co_u32_e32 v165, vcc, 0, v13, vcc
	flat_load_dwordx4 v[160:163], v[14:15]
	s_nop 0
	flat_load_dwordx4 v[164:167], v[164:165]
	v_add_co_u32_e32 v14, vcc, 0x28018000, v12
	s_nop 1
	v_addc_co_u32_e32 v15, vcc, 0, v13, vcc
	v_add_co_u32_e32 v12, vcc, 0x2801c000, v12
	s_nop 1
	v_addc_co_u32_e32 v13, vcc, 0, v13, vcc
	flat_load_dwordx4 v[168:171], v[14:15]
	flat_load_dwordx4 v[172:175], v[12:13]
